# v10 with the softmax VALU segment at priority 2 (MFMA clusters at 1)
# baseline (speedup 1.0000x reference)
; #define SBAR() __builtin_amdgcn_sched_barrier(0)
; template <int DQK, int MODE, bool PIPE>
; DI void attn_core(const u16* __restrict__ Qg, const u16* __restrict__ Kg, const u16* __restrict__ Vtg, int ntiles,
;                   int kr_lo, int rs, int r_q, int c_q, int cs, const float* biasL, char* lds, f32x16 (&o)[4], float& l_out, int tid) {
;     ...
;   auto qk = [&](int t, f32x16& p0, f32x16& p1) {
;     const char* kb = lds + (t & 1) * A_BUF + r32 * KSTR + h * 16;
;     if (MODE != 0) {
; #pragma unroll
;       for (int i = 0; i < 16; ++i) { p0[i] = 0.f; p1[i] = 0.f; }
;     }
;     if (MODE == 0) {
;       constexpr int R = 4, NF = 2 * NKS;
;       const unsigned kaddr = (unsigned)(size_t)kb;
;       bf16x8 f[R];
;       SBAR();
;       f[0] = lds_rd128<0>(kaddr); f[1] = lds_rd128<32 * KSTR>(kaddr); f[2] = lds_rd128<32>(kaddr); f[3] = lds_rd128<32 * KSTR + 32>(kaddr);
;       SBAR();
;       __builtin_amdgcn_s_setprio(1);
;       QkStep<DQK, 0, NF, R>::run(kaddr, f, qf, p0, p1, negm);
;       __builtin_amdgcn_s_setprio(0);
;     ...
;     asm volatile("s_nop 7\n\ts_nop 7\n\ts_nop 7" ::: "memory");
;     if (!NEGM && __any(m != 0.f)) {
; #pragma unroll
;       for (int i = 0; i < 16; ++i) {
;         asm("v_sub_f32 %0, %1, %2" : "=v"(p0[i]) : "v"(p0[i]), "v"(m));
;         asm("v_sub_f32 %0, %1, %2" : "=v"(p1[i]) : "v"(p1[i]), "v"(m));
;       }
;     }
.LBB0_821:
	s_bitcmp1_b32 s6, 0
	s_cselect_b32 s7, 0xa800, 0
	s_add_i32 s19, s7, 0
	v_add3_u32 v244, s19, v225, v0
	ds_read_b128 v[66:69], v244 offset:0
	ds_read_b128 v[82:85], v244 offset:0x3200
	ds_read_b128 v[228:231], v244 offset:32
	ds_read_b128 v[232:235], v244 offset:0x3220
	s_setprio 1
	s_waitcnt lgkmcnt(2)
	v_mfma_f32_32x32x16_bf16 v[66:81], v[66:69], v[98:101], 0
	ds_read_b128 v[236:239], v244 offset:64
	v_mfma_f32_32x32x16_bf16 v[82:97], v[82:85], v[98:101], 0
	ds_read_b128 v[240:243], v244 offset:0x3240
	s_waitcnt lgkmcnt(2)
	v_mfma_f32_32x32x16_bf16 v[66:81], v[228:231], v[102:105], v[66:81]
	ds_read_b128 v[228:231], v244 offset:0x60
	v_mfma_f32_32x32x16_bf16 v[82:97], v[232:235], v[102:105], v[82:97]
	ds_read_b128 v[232:235], v244 offset:0x3260
	s_waitcnt lgkmcnt(2)
	v_mfma_f32_32x32x16_bf16 v[66:81], v[236:239], v[106:109], v[66:81]
	ds_read_b128 v[236:239], v244 offset:0x80
	v_mfma_f32_32x32x16_bf16 v[82:97], v[240:243], v[106:109], v[82:97]
	ds_read_b128 v[240:243], v244 offset:0x3280
	s_waitcnt lgkmcnt(2)
	v_mfma_f32_32x32x16_bf16 v[66:81], v[228:231], v[110:113], v[66:81]
	ds_read_b128 v[228:231], v244 offset:0xa0
	v_mfma_f32_32x32x16_bf16 v[82:97], v[232:235], v[110:113], v[82:97]
	ds_read_b128 v[232:235], v244 offset:0x32a0
	s_waitcnt lgkmcnt(2)
	v_mfma_f32_32x32x16_bf16 v[66:81], v[236:239], v[114:117], v[66:81]
	ds_read_b128 v[236:239], v244 offset:0xc0
	v_mfma_f32_32x32x16_bf16 v[82:97], v[240:243], v[114:117], v[82:97]
	ds_read_b128 v[240:243], v244 offset:0x32c0
	s_waitcnt lgkmcnt(2)
	v_mfma_f32_32x32x16_bf16 v[66:81], v[228:231], v[118:121], v[66:81]
	ds_read_b128 v[228:231], v244 offset:0xe0
	v_mfma_f32_32x32x16_bf16 v[82:97], v[232:235], v[118:121], v[82:97]
	ds_read_b128 v[232:235], v244 offset:0x32e0
	s_waitcnt lgkmcnt(2)
	v_mfma_f32_32x32x16_bf16 v[66:81], v[236:239], v[122:125], v[66:81]
	ds_read_b128 v[236:239], v244 offset:0x100
	v_mfma_f32_32x32x16_bf16 v[82:97], v[240:243], v[122:125], v[82:97]
	ds_read_b128 v[240:243], v244 offset:0x3300
	s_waitcnt lgkmcnt(2)
	v_mfma_f32_32x32x16_bf16 v[66:81], v[228:231], v[126:129], v[66:81]
	ds_read_b128 v[228:231], v244 offset:0x120
	v_mfma_f32_32x32x16_bf16 v[82:97], v[232:235], v[126:129], v[82:97]
	ds_read_b128 v[232:235], v244 offset:0x3320
	s_waitcnt lgkmcnt(2)
	v_mfma_f32_32x32x16_bf16 v[66:81], v[236:239], v[130:133], v[66:81]
	ds_read_b128 v[236:239], v244 offset:0x140
	v_mfma_f32_32x32x16_bf16 v[82:97], v[240:243], v[130:133], v[82:97]
	ds_read_b128 v[240:243], v244 offset:0x3340
	s_waitcnt lgkmcnt(2)
	v_mfma_f32_32x32x16_bf16 v[66:81], v[228:231], v[134:137], v[66:81]
	ds_read_b128 v[228:231], v244 offset:0x160
	v_mfma_f32_32x32x16_bf16 v[82:97], v[232:235], v[134:137], v[82:97]
	ds_read_b128 v[232:235], v244 offset:0x3360
	s_waitcnt lgkmcnt(2)
	v_mfma_f32_32x32x16_bf16 v[66:81], v[236:239], v[138:141], v[66:81]
	v_mfma_f32_32x32x16_bf16 v[82:97], v[240:243], v[138:141], v[82:97]
	s_waitcnt lgkmcnt(0)
	v_mfma_f32_32x32x16_bf16 v[66:81], v[228:231], v[142:145], v[66:81]
	v_mfma_f32_32x32x16_bf16 v[82:97], v[232:235], v[142:145], v[82:97]
	s_setprio 2
	s_nop 7
	s_nop 7
	v_cmp_neq_f32_e32 vcc, 0, v227
	s_cbranch_vccz .LBB0_823
	v_sub_f32 v66, v66, v227
	v_sub_f32 v82, v82, v227
	v_sub_f32 v67, v67, v227
	v_sub_f32 v83, v83, v227
	v_sub_f32 v68, v68, v227
	v_sub_f32 v84, v84, v227
	v_sub_f32 v69, v69, v227
	v_sub_f32 v85, v85, v227
	v_sub_f32 v70, v70, v227
	v_sub_f32 v86, v86, v227
	v_sub_f32 v71, v71, v227
	v_sub_f32 v87, v87, v227
	v_sub_f32 v72, v72, v227
	v_sub_f32 v88, v88, v227
	v_sub_f32 v73, v73, v227
	v_sub_f32 v89, v89, v227
	v_sub_f32 v74, v74, v227
	v_sub_f32 v90, v90, v227
	v_sub_f32 v75, v75, v227
	v_sub_f32 v91, v91, v227
	v_sub_f32 v76, v76, v227
	v_sub_f32 v92, v92, v227
	v_sub_f32 v77, v77, v227
	v_sub_f32 v93, v93, v227
	v_sub_f32 v78, v78, v227
	v_sub_f32 v94, v94, v227
	v_sub_f32 v79, v79, v227
	v_sub_f32 v95, v95, v227
	v_sub_f32 v80, v80, v227
	v_sub_f32 v96, v96, v227
	v_sub_f32 v81, v81, v227
	v_sub_f32 v97, v97, v227

; template <int DQK, int MODE, bool PIPE>
; DI void attn_core(const u16* __restrict__ Qg, const u16* __restrict__ Kg, const u16* __restrict__ Vtg, int ntiles,
;                   int kr_lo, int rs, int r_q, int c_q, int cs, const float* biasL, char* lds, f32x16 (&o)[4], float& l_out, int tid) {
;     ...
;   auto qk = [&](int t, f32x16& p0, f32x16& p1) {
;     const char* kb = lds + (t & 1) * A_BUF + r32 * KSTR + h * 16;
;     if (MODE != 0) {
; #pragma unroll
;       for (int i = 0; i < 16; ++i) { p0[i] = 0.f; p1[i] = 0.f; }
;     }
;     if (MODE == 0) {
;       constexpr int R = 4, NF = 2 * NKS;
;       const unsigned kaddr = (unsigned)(size_t)kb;
;       bf16x8 f[R];
;       SBAR();
;       f[0] = lds_rd128<0>(kaddr); f[1] = lds_rd128<32 * KSTR>(kaddr); f[2] = lds_rd128<32>(kaddr); f[3] = lds_rd128<32 * KSTR + 32>(kaddr);
;       SBAR();
;       __builtin_amdgcn_s_setprio(1);
;       QkStep<DQK, 0, NF, R>::run(kaddr, f, qf, p0, p1, negm);
;       __builtin_amdgcn_s_setprio(0);
;     ...
;     float tmx;
;     {
;       float u[11];
; #pragma unroll
;       for (int i = 0; i < 5; ++i) {
;         asm("v_max3_f32 %0, %1, %2, %3" : "=v"(u[2 * i]) : "v"(p0[3 * i]), "v"(p0[3 * i + 1]), "v"(p0[3 * i + 2]));
;         asm("v_max3_f32 %0, %1, %2, %3" : "=v"(u[2 * i + 1]) : "v"(p1[3 * i]), "v"(p1[3 * i + 1]), "v"(p1[3 * i + 2]));
;       }
;       asm("v_max3_f32 %0, %1, %2, %3" : "=v"(u[10]) : "v"(p0[15]), "v"(p1[15]), "v"(u[0]));
;       float w0, w1, w2, w3;
;       asm("v_max3_f32 %0, %1, %2, %3" : "=v"(w0) : "v"(u[1]), "v"(u[2]), "v"(u[3]));
;       asm("v_max3_f32 %0, %1, %2, %3" : "=v"(w1) : "v"(u[4]), "v"(u[5]), "v"(u[6]));
;       asm("v_max3_f32 %0, %1, %2, %3" : "=v"(w2) : "v"(u[7]), "v"(u[8]), "v"(u[9]));
;       asm("v_max3_f32 %0, %1, %2, %3" : "=v"(w3) : "v"(u[10]), "v"(w0), "v"(w1));
;       asm("v_max_f32 %0, %1, %2" : "=v"(tmx) : "v"(w2), "v"(w3));
;     }
;     const bool t0 = (t == 0);
;     if (__any(tmx > THR || (t0 && tmx < -THR))) {
;       tmx = fmaxf(tmx, __shfl_xor(tmx, 32));
;       const float delta = t0 ? tmx : fmaxf(tmx, 0.f);
;       const float alpha = __builtin_amdgcn_exp2f(-fmaxf(delta, 0.f));
;       m += delta; l *= alpha;
; #pragma unroll
;       for (int d = 0; d < 4; ++d)
; #pragma unroll
;         for (int i = 0; i < 16; ++i) o[d][i] *= alpha;
; #pragma unroll
;       for (int i = 0; i < 16; ++i) { p0[i] -= delta; p1[i] -= delta; }
.LBB0_842:
	s_bitcmp1_b32 s15, 0
	s_cselect_b32 s15, 0xa800, 0
	v_add3_u32 v177, s15, v167, v0
	ds_read_b128 v[98:101], v177 offset:0
	ds_read_b128 v[216:219], v177 offset:0x1200
	ds_read_b128 v[220:223], v177 offset:32
	ds_read_b128 v[224:227], v177 offset:0x1220
	s_setprio 1
	s_waitcnt lgkmcnt(2)
	v_mfma_f32_32x32x16_bf16 v[82:97], v[98:101], v[114:117], v[18:33]
	ds_read_b128 v[228:231], v177 offset:64
	v_mfma_f32_32x32x16_bf16 v[98:113], v[216:219], v[114:117], v[18:33]
	ds_read_b128 v[216:219], v177 offset:0x1240
	s_waitcnt lgkmcnt(2)
	v_mfma_f32_32x32x16_bf16 v[82:97], v[220:223], v[118:121], v[82:97]
	ds_read_b128 v[220:223], v177 offset:0x60
	v_mfma_f32_32x32x16_bf16 v[98:113], v[224:227], v[118:121], v[98:113]
	ds_read_b128 v[224:227], v177 offset:0x1260
	s_waitcnt lgkmcnt(2)
	v_mfma_f32_32x32x16_bf16 v[82:97], v[228:231], v[122:125], v[82:97]
	v_mfma_f32_32x32x16_bf16 v[98:113], v[216:219], v[122:125], v[98:113]
	s_waitcnt lgkmcnt(0)
	v_mfma_f32_32x32x16_bf16 v[82:97], v[220:223], v[126:129], v[82:97]
	v_mfma_f32_32x32x16_bf16 v[98:113], v[224:227], v[126:129], v[98:113]
	s_setprio 2
	v_max3_f32 v177, v82, v83, v84
	s_nop 7
	s_nop 7
	v_max3_f32 v199, v98, v99, v100
	v_max3_f32 v216, v85, v86, v87
	v_max3_f32 v217, v101, v102, v103
	v_max3_f32 v218, v88, v89, v90
	v_max3_f32 v177, v97, v113, v177
	v_max3_f32 v219, v104, v105, v106
	v_max3_f32 v220, v91, v92, v93
	v_max3_f32 v221, v107, v108, v109
	v_max3_f32 v199, v199, v216, v217
	v_max3_f32 v222, v94, v95, v96
	v_max3_f32 v223, v110, v111, v112
	v_max3_f32 v216, v218, v219, v220
	v_max3_f32 v217, v221, v222, v223
	v_max3_f32 v177, v177, v199, v216
	v_max_f32 v177, v217, v177
	v_cmp_lt_f32_e32 vcc, s66, v177
	s_cbranch_vccz .LBB0_844
	v_and_b32_e32 v19, 64, v189
	v_xor_b32_e32 v18, 32, v189
	v_add_u32_e32 v19, 64, v19
	v_cmp_lt_i32_e32 vcc, v18, v19
	s_nop 1
	v_cndmask_b32_e32 v18, v189, v18, vcc
	v_lshlrev_b32_e32 v18, 2, v18
	ds_bpermute_b32 v18, v18, v177
	s_waitcnt lgkmcnt(0)
	v_max3_f32 v18, v177, v18, 0
	v_exp_f32_e64 v20, -v18
	v_add_f32_e32 v175, v175, v18
	v_pk_add_f32 v[82:83], v[82:83], v[18:19] op_sel_hi:[1,0] neg_lo:[0,1] neg_hi:[0,1]
	v_pk_add_f32 v[98:99], v[98:99], v[18:19] op_sel_hi:[1,0] neg_lo:[0,1] neg_hi:[0,1]
	v_pk_add_f32 v[84:85], v[84:85], v[18:19] op_sel_hi:[1,0] neg_lo:[0,1] neg_hi:[0,1]
	v_pk_add_f32 v[100:101], v[100:101], v[18:19] op_sel_hi:[1,0] neg_lo:[0,1] neg_hi:[0,1]
	v_pk_add_f32 v[86:87], v[86:87], v[18:19] op_sel_hi:[1,0] neg_lo:[0,1] neg_hi:[0,1]
	v_pk_add_f32 v[102:103], v[102:103], v[18:19] op_sel_hi:[1,0] neg_lo:[0,1] neg_hi:[0,1]
	v_pk_add_f32 v[88:89], v[88:89], v[18:19] op_sel_hi:[1,0] neg_lo:[0,1] neg_hi:[0,1]
	v_pk_add_f32 v[104:105], v[104:105], v[18:19] op_sel_hi:[1,0] neg_lo:[0,1] neg_hi:[0,1]
	v_pk_add_f32 v[90:91], v[90:91], v[18:19] op_sel_hi:[1,0] neg_lo:[0,1] neg_hi:[0,1]
	v_pk_add_f32 v[106:107], v[106:107], v[18:19] op_sel_hi:[1,0] neg_lo:[0,1] neg_hi:[0,1]
	v_pk_add_f32 v[92:93], v[92:93], v[18:19] op_sel_hi:[1,0] neg_lo:[0,1] neg_hi:[0,1]
	v_pk_add_f32 v[108:109], v[108:109], v[18:19] op_sel_hi:[1,0] neg_lo:[0,1] neg_hi:[0,1]
	v_pk_add_f32 v[94:95], v[94:95], v[18:19] op_sel_hi:[1,0] neg_lo:[0,1] neg_hi:[0,1]
	v_pk_add_f32 v[110:111], v[110:111], v[18:19] op_sel_hi:[1,0] neg_lo:[0,1] neg_hi:[0,1]
	v_pk_add_f32 v[96:97], v[96:97], v[18:19] op_sel_hi:[1,0] neg_lo:[0,1] neg_hi:[0,1]
	v_pk_add_f32 v[112:113], v[112:113], v[18:19] op_sel_hi:[1,0] neg_lo:[0,1] neg_hi:[0,1]
	v_xor_b32_e32 v18, 0x80000000, v175
	v_mul_f32_e32 v176, v176, v20
	v_pk_mul_f32 v[80:81], v[80:81], v[20:21] op_sel_hi:[1,0]
	v_pk_mul_f32 v[78:79], v[78:79], v[20:21] op_sel_hi:[1,0]
	v_pk_mul_f32 v[76:77], v[76:77], v[20:21] op_sel_hi:[1,0]
	v_pk_mul_f32 v[74:75], v[74:75], v[20:21] op_sel_hi:[1,0]
	v_pk_mul_f32 v[72:73], v[72:73], v[20:21] op_sel_hi:[1,0]
	v_pk_mul_f32 v[70:71], v[70:71], v[20:21] op_sel_hi:[1,0]
	v_pk_mul_f32 v[68:69], v[68:69], v[20:21] op_sel_hi:[1,0]
	v_pk_mul_f32 v[66:67], v[66:67], v[20:21] op_sel_hi:[1,0]
	v_pk_mul_f32 v[64:65], v[64:65], v[20:21] op_sel_hi:[1,0]
	v_pk_mul_f32 v[62:63], v[62:63], v[20:21] op_sel_hi:[1,0]
	v_pk_mul_f32 v[60:61], v[60:61], v[20:21] op_sel_hi:[1,0]
	v_pk_mul_f32 v[58:59], v[58:59], v[20:21] op_sel_hi:[1,0]
	v_pk_mul_f32 v[56:57], v[56:57], v[20:21] op_sel_hi:[1,0]
	v_pk_mul_f32 v[54:55], v[54:55], v[20:21] op_sel_hi:[1,0]
	v_pk_mul_f32 v[52:53], v[52:53], v[20:21] op_sel_hi:[1,0]
	v_pk_mul_f32 v[50:51], v[50:51], v[20:21] op_sel_hi:[1,0]
	v_pk_mul_f32 v[48:49], v[48:49], v[20:21] op_sel_hi:[1,0]
	v_pk_mul_f32 v[46:47], v[46:47], v[20:21] op_sel_hi:[1,0]
	v_pk_mul_f32 v[44:45], v[44:45], v[20:21] op_sel_hi:[1,0]
	v_pk_mul_f32 v[42:43], v[42:43], v[20:21] op_sel_hi:[1,0]
	v_pk_mul_f32 v[40:41], v[40:41], v[20:21] op_sel_hi:[1,0]
	v_pk_mul_f32 v[38:39], v[38:39], v[20:21] op_sel_hi:[1,0]
	v_pk_mul_f32 v[36:37], v[36:37], v[20:21] op_sel_hi:[1,0]
	v_pk_mul_f32 v[34:35], v[34:35], v[20:21] op_sel_hi:[1,0]
	v_pk_mul_f32 v[16:17], v[16:17], v[20:21] op_sel_hi:[1,0]
	v_pk_mul_f32 v[14:15], v[14:15], v[20:21] op_sel_hi:[1,0]
	v_pk_mul_f32 v[12:13], v[12:13], v[20:21] op_sel_hi:[1,0]
	v_pk_mul_f32 v[10:11], v[10:11], v[20:21] op_sel_hi:[1,0]
	v_pk_mul_f32 v[8:9], v[8:9], v[20:21] op_sel_hi:[1,0]
	v_pk_mul_f32 v[6:7], v[6:7], v[20:21] op_sel_hi:[1,0]
	v_pk_mul_f32 v[4:5], v[4:5], v[20:21] op_sel_hi:[1,0]
	v_pk_mul_f32 v[2:3], v[2:3], v[20:21] op_sel_hi:[1,0]
	v_mov_b32_e32 v19, v18
	v_mov_b32_e32 v20, v18
	v_mov_b32_e32 v21, v18
	v_mov_b32_e32 v22, v18
	v_mov_b32_e32 v23, v18
	v_mov_b32_e32 v24, v18
	v_mov_b32_e32 v25, v18
	v_mov_b32_e32 v26, v18
	v_mov_b32_e32 v27, v18
	v_mov_b32_e32 v28, v18
	v_mov_b32_e32 v29, v18
	v_mov_b32_e32 v30, v18
	v_mov_b32_e32 v31, v18
	v_mov_b32_e32 v32, v18
	v_mov_b32_e32 v33, v18

; template <int DQK, int MODE, bool PIPE>
; DI void attn_core(const u16* __restrict__ Qg, const u16* __restrict__ Kg, const u16* __restrict__ Vtg, int ntiles,
;                   int kr_lo, int rs, int r_q, int c_q, int cs, const float* biasL, char* lds, f32x16 (&o)[4], float& l_out, int tid) {
;     ...
;   auto qk = [&](int t, f32x16& p0, f32x16& p1) {
;     const char* kb = lds + (t & 1) * A_BUF + r32 * KSTR + h * 16;
;     if (MODE != 0) {
; #pragma unroll
;       for (int i = 0; i < 16; ++i) { p0[i] = 0.f; p1[i] = 0.f; }
;     }
;     if (MODE == 0) {
;       constexpr int R = 4, NF = 2 * NKS;
;       const unsigned kaddr = (unsigned)(size_t)kb;
;       bf16x8 f[R];
;       SBAR();
;       f[0] = lds_rd128<0>(kaddr); f[1] = lds_rd128<32 * KSTR>(kaddr); f[2] = lds_rd128<32>(kaddr); f[3] = lds_rd128<32 * KSTR + 32>(kaddr);
;       SBAR();
;       __builtin_amdgcn_s_setprio(1);
;       QkStep<DQK, 0, NF, R>::run(kaddr, f, qf, p0, p1, negm);
;       __builtin_amdgcn_s_setprio(0);
;     ...
;     float tmx;
;     {
;       float u[11];
; #pragma unroll
;       for (int i = 0; i < 5; ++i) {
;         asm("v_max3_f32 %0, %1, %2, %3" : "=v"(u[2 * i]) : "v"(p0[3 * i]), "v"(p0[3 * i + 1]), "v"(p0[3 * i + 2]));
;         asm("v_max3_f32 %0, %1, %2, %3" : "=v"(u[2 * i + 1]) : "v"(p1[3 * i]), "v"(p1[3 * i + 1]), "v"(p1[3 * i + 2]));
;       }
;       asm("v_max3_f32 %0, %1, %2, %3" : "=v"(u[10]) : "v"(p0[15]), "v"(p1[15]), "v"(u[0]));
;       float w0, w1, w2, w3;
;       asm("v_max3_f32 %0, %1, %2, %3" : "=v"(w0) : "v"(u[1]), "v"(u[2]), "v"(u[3]));
;       asm("v_max3_f32 %0, %1, %2, %3" : "=v"(w1) : "v"(u[4]), "v"(u[5]), "v"(u[6]));
;       asm("v_max3_f32 %0, %1, %2, %3" : "=v"(w2) : "v"(u[7]), "v"(u[8]), "v"(u[9]));
;       asm("v_max3_f32 %0, %1, %2, %3" : "=v"(w3) : "v"(u[10]), "v"(w0), "v"(w1));
;       asm("v_max_f32 %0, %1, %2" : "=v"(tmx) : "v"(w2), "v"(w3));
;     }
;     const bool t0 = (t == 0);
;     if (__any(tmx > THR || (t0 && tmx < -THR))) {
;       tmx = fmaxf(tmx, __shfl_xor(tmx, 32));
;       const float delta = t0 ? tmx : fmaxf(tmx, 0.f);
;       const float alpha = __builtin_amdgcn_exp2f(-fmaxf(delta, 0.f));
;       m += delta; l *= alpha;
; #pragma unroll
;       for (int d = 0; d < 4; ++d)
; #pragma unroll
;         for (int i = 0; i < 16; ++i) o[d][i] *= alpha;
; #pragma unroll
;       for (int i = 0; i < 16; ++i) { p0[i] -= delta; p1[i] -= delta; }
.LBB0_858:
	s_bitcmp1_b32 s12, 0
	s_cselect_b32 s12, 0xa800, 0
	v_add3_u32 v160, s12, v167, v0
	ds_read_b128 v[98:101], v160 offset:0
	ds_read_b128 v[156:159], v160 offset:0x1200
	ds_read_b128 v[170:173], v160 offset:32
	ds_read_b128 v[174:177], v160 offset:0x1220
	s_setprio 1
	s_waitcnt lgkmcnt(2)
	v_mfma_f32_32x32x16_bf16 v[82:97], v[98:101], v[114:117], v[34:49]
	ds_read_b128 v[216:219], v160 offset:64
	v_mfma_f32_32x32x16_bf16 v[98:113], v[156:159], v[114:117], v[34:49]
	ds_read_b128 v[156:159], v160 offset:0x1240
	s_waitcnt lgkmcnt(2)
	v_mfma_f32_32x32x16_bf16 v[82:97], v[170:173], v[118:121], v[82:97]
	ds_read_b128 v[170:173], v160 offset:0x60
	v_mfma_f32_32x32x16_bf16 v[98:113], v[174:177], v[118:121], v[98:113]
	ds_read_b128 v[174:177], v160 offset:0x1260
	s_waitcnt lgkmcnt(2)
	v_mfma_f32_32x32x16_bf16 v[82:97], v[216:219], v[122:125], v[82:97]
	v_mfma_f32_32x32x16_bf16 v[98:113], v[156:159], v[122:125], v[98:113]
	s_waitcnt lgkmcnt(0)
	v_mfma_f32_32x32x16_bf16 v[82:97], v[170:173], v[126:129], v[82:97]
	v_mfma_f32_32x32x16_bf16 v[98:113], v[174:177], v[126:129], v[98:113]
	s_setprio 2
	v_max3_f32 v156, v82, v83, v84
	s_nop 7
	s_nop 7
	v_max3_f32 v157, v98, v99, v100
	v_max3_f32 v158, v85, v86, v87
	v_max3_f32 v159, v101, v102, v103
	v_max3_f32 v160, v88, v89, v90
	v_max3_f32 v156, v97, v113, v156
	v_max3_f32 v161, v104, v105, v106
	v_max3_f32 v163, v91, v92, v93
	v_max3_f32 v169, v107, v108, v109
	v_max3_f32 v157, v157, v158, v159
	v_max3_f32 v170, v94, v95, v96
	v_max3_f32 v171, v110, v111, v112
	v_max3_f32 v158, v160, v161, v163
	v_max3_f32 v159, v169, v170, v171
	v_max3_f32 v156, v156, v157, v158
	v_max_f32 v156, v159, v156
	v_cmp_lt_f32_e32 vcc, s66, v156
	s_cbranch_vccz .LBB0_860
	ds_bpermute_b32 v34, v162, v156
	s_waitcnt lgkmcnt(0)
	v_max3_f32 v34, v156, v34, 0
	v_exp_f32_e64 v36, -v34
	v_add_f32_e32 v154, v154, v34
	v_pk_add_f32 v[82:83], v[82:83], v[34:35] op_sel_hi:[1,0] neg_lo:[0,1] neg_hi:[0,1]
	v_pk_add_f32 v[98:99], v[98:99], v[34:35] op_sel_hi:[1,0] neg_lo:[0,1] neg_hi:[0,1]
	v_pk_add_f32 v[84:85], v[84:85], v[34:35] op_sel_hi:[1,0] neg_lo:[0,1] neg_hi:[0,1]
	v_pk_add_f32 v[100:101], v[100:101], v[34:35] op_sel_hi:[1,0] neg_lo:[0,1] neg_hi:[0,1]
	v_pk_add_f32 v[86:87], v[86:87], v[34:35] op_sel_hi:[1,0] neg_lo:[0,1] neg_hi:[0,1]
	v_pk_add_f32 v[102:103], v[102:103], v[34:35] op_sel_hi:[1,0] neg_lo:[0,1] neg_hi:[0,1]
	v_pk_add_f32 v[88:89], v[88:89], v[34:35] op_sel_hi:[1,0] neg_lo:[0,1] neg_hi:[0,1]
	v_pk_add_f32 v[104:105], v[104:105], v[34:35] op_sel_hi:[1,0] neg_lo:[0,1] neg_hi:[0,1]
	v_pk_add_f32 v[90:91], v[90:91], v[34:35] op_sel_hi:[1,0] neg_lo:[0,1] neg_hi:[0,1]
	v_pk_add_f32 v[106:107], v[106:107], v[34:35] op_sel_hi:[1,0] neg_lo:[0,1] neg_hi:[0,1]
	v_pk_add_f32 v[92:93], v[92:93], v[34:35] op_sel_hi:[1,0] neg_lo:[0,1] neg_hi:[0,1]
	v_pk_add_f32 v[108:109], v[108:109], v[34:35] op_sel_hi:[1,0] neg_lo:[0,1] neg_hi:[0,1]
	v_pk_add_f32 v[94:95], v[94:95], v[34:35] op_sel_hi:[1,0] neg_lo:[0,1] neg_hi:[0,1]
	v_pk_add_f32 v[110:111], v[110:111], v[34:35] op_sel_hi:[1,0] neg_lo:[0,1] neg_hi:[0,1]
	v_pk_add_f32 v[96:97], v[96:97], v[34:35] op_sel_hi:[1,0] neg_lo:[0,1] neg_hi:[0,1]
	v_pk_add_f32 v[112:113], v[112:113], v[34:35] op_sel_hi:[1,0] neg_lo:[0,1] neg_hi:[0,1]
	v_xor_b32_e32 v34, 0x80000000, v154
	v_mul_f32_e32 v155, v155, v36
	v_pk_mul_f32 v[80:81], v[80:81], v[36:37] op_sel_hi:[1,0]
	v_pk_mul_f32 v[78:79], v[78:79], v[36:37] op_sel_hi:[1,0]
	v_pk_mul_f32 v[76:77], v[76:77], v[36:37] op_sel_hi:[1,0]
	v_pk_mul_f32 v[74:75], v[74:75], v[36:37] op_sel_hi:[1,0]
	v_pk_mul_f32 v[72:73], v[72:73], v[36:37] op_sel_hi:[1,0]
	v_pk_mul_f32 v[70:71], v[70:71], v[36:37] op_sel_hi:[1,0]
	v_pk_mul_f32 v[68:69], v[68:69], v[36:37] op_sel_hi:[1,0]
	v_pk_mul_f32 v[66:67], v[66:67], v[36:37] op_sel_hi:[1,0]
	v_pk_mul_f32 v[64:65], v[64:65], v[36:37] op_sel_hi:[1,0]
	v_pk_mul_f32 v[62:63], v[62:63], v[36:37] op_sel_hi:[1,0]
	v_pk_mul_f32 v[60:61], v[60:61], v[36:37] op_sel_hi:[1,0]
	v_pk_mul_f32 v[58:59], v[58:59], v[36:37] op_sel_hi:[1,0]
	v_pk_mul_f32 v[56:57], v[56:57], v[36:37] op_sel_hi:[1,0]
	v_pk_mul_f32 v[54:55], v[54:55], v[36:37] op_sel_hi:[1,0]
	v_pk_mul_f32 v[52:53], v[52:53], v[36:37] op_sel_hi:[1,0]
	v_pk_mul_f32 v[50:51], v[50:51], v[36:37] op_sel_hi:[1,0]
	v_pk_mul_f32 v[32:33], v[32:33], v[36:37] op_sel_hi:[1,0]
	v_pk_mul_f32 v[30:31], v[30:31], v[36:37] op_sel_hi:[1,0]
	v_pk_mul_f32 v[28:29], v[28:29], v[36:37] op_sel_hi:[1,0]
	v_pk_mul_f32 v[26:27], v[26:27], v[36:37] op_sel_hi:[1,0]
	v_pk_mul_f32 v[24:25], v[24:25], v[36:37] op_sel_hi:[1,0]
	v_pk_mul_f32 v[22:23], v[22:23], v[36:37] op_sel_hi:[1,0]
	v_pk_mul_f32 v[20:21], v[20:21], v[36:37] op_sel_hi:[1,0]
	v_pk_mul_f32 v[18:19], v[18:19], v[36:37] op_sel_hi:[1,0]
	v_pk_mul_f32 v[16:17], v[16:17], v[36:37] op_sel_hi:[1,0]
	v_pk_mul_f32 v[14:15], v[14:15], v[36:37] op_sel_hi:[1,0]
	v_pk_mul_f32 v[12:13], v[12:13], v[36:37] op_sel_hi:[1,0]
	v_pk_mul_f32 v[10:11], v[10:11], v[36:37] op_sel_hi:[1,0]
	v_pk_mul_f32 v[8:9], v[8:9], v[36:37] op_sel_hi:[1,0]
	v_pk_mul_f32 v[6:7], v[6:7], v[36:37] op_sel_hi:[1,0]
	v_pk_mul_f32 v[4:5], v[4:5], v[36:37] op_sel_hi:[1,0]
	v_pk_mul_f32 v[2:3], v[2:3], v[36:37] op_sel_hi:[1,0]
	v_mov_b32_e32 v35, v34
	v_mov_b32_e32 v36, v34
	v_mov_b32_e32 v37, v34
	v_mov_b32_e32 v38, v34
	v_mov_b32_e32 v39, v34
	v_mov_b32_e32 v40, v34
	v_mov_b32_e32 v41, v34
	v_mov_b32_e32 v42, v34
	v_mov_b32_e32 v43, v34
	v_mov_b32_e32 v44, v34
	v_mov_b32_e32 v45, v34
	v_mov_b32_e32 v46, v34
	v_mov_b32_e32 v47, v34
	v_mov_b32_e32 v48, v34
	v_mov_b32_e32 v49, v34
